# NA latent items: one dummy dword load next to the item's own Q loads touches the next item's Q rows (L2 prefetch)
# speedup vs baseline: 1.0042x; 1.0042x over previous
.LBB0_1093:
	s_or_b64 exec, exec, s[0:1]
	s_lshl_b32 s1, s71, 2
	s_and_b32 s86, s1, 60
	v_sub_u32_e64 v0, s86, 4 clamp
	s_ashr_i32 s0, s71, 8
	v_readfirstlane_b32 s87, v0
	v_sub_u32_e64 v0, s86, 1 clamp
	v_readlane_b32 s78, v238, 14
	v_readfirstlane_b32 s1, v0
	s_min_u32 s1, s1, 56
	s_sub_i32 s84, s1, s87
	s_add_i32 s80, s84, 7
	s_and_b32 s91, s80, -2
	s_ashr_i32 s1, s0, 31
	s_add_i32 s85, s91, 6
	s_lshl_b64 s[72:73], s[0:1], 12
	s_add_u32 s72, s72, 0x2000
	s_addc_u32 s73, s73, 0
	s_lshl_b32 s71, s86, 6
	s_or_b32 s74, s72, s71
	s_mov_b32 s75, s73
	s_lshl_b64 s[74:75], s[74:75], 11
	v_readlane_b32 s79, v238, 15
	s_add_u32 s71, s78, s74
	s_addc_u32 s77, s79, s75
	s_lshl_b32 s78, s70, 7
	s_add_u32 s70, s71, s78
	s_addc_u32 s71, s77, 0
	s_lshl_b64 s[0:1], s[0:1], 19
	v_readlane_b32 s77, v238, 17
	s_add_u32 s77, s77, s0
	v_readlane_b32 s79, v238, 18
	s_addc_u32 s79, s79, s1
	s_add_u32 s82, s77, s78
	s_addc_u32 s83, s79, 0
	v_readlane_b32 s77, v238, 19
	s_add_u32 s0, s77, s0
	v_readlane_b32 s77, v238, 20
	s_addc_u32 s1, s77, s1
	s_add_u32 s92, s0, s78
	s_addc_u32 s93, s1, 0
	s_lshl_b64 s[0:1], s[72:73], 11
	s_add_u32 s72, s81, s0
	s_addc_u32 s73, s88, s1
	s_add_u32 s96, s72, s78
	s_addc_u32 s97, s73, 0
	s_add_u32 s0, s89, s0
	s_addc_u32 s1, s94, s1
	s_add_u32 s0, s0, s78
	s_addc_u32 s1, s1, 0
	s_add_u32 s72, s95, s74
	v_readlane_b32 s73, v238, 16
	v_lshl_add_u64 v[0:1], s[70:71], 0, v[156:157]
	v_add_u32_e32 v197, s86, v181
	s_addc_u32 s73, s73, s75
	v_lshl_add_u64 v[160:161], v[0:1], 0, v[152:153]
	v_sub_u32_e64 v0, v197, 4 clamp
	s_add_u32 s94, s72, s78
	v_min_u32_e32 v175, 56, v0
	v_lshl_add_u64 v[0:1], s[82:83], 0, v[158:159]
	s_addc_u32 s95, s73, 0
	v_readfirstlane_b32 s72, v192
	v_lshl_add_u64 v[162:163], v[0:1], 0, v[148:149]
	v_lshl_add_u64 v[0:1], s[92:93], 0, v[158:159]
	s_bitcmp0_b32 s72, 6
	v_lshl_add_u64 v[164:165], v[0:1], 0, v[148:149]
	s_mov_b64 s[70:71], -1
	s_waitcnt lgkmcnt(0)
	s_barrier
	s_cbranch_scc1 .LBB0_1320
	global_load_dwordx4 v[132:135], v[164:165], off
	global_load_dwordx4 v[128:131], v[162:163], off
	global_load_dwordx4 v[124:127], v[160:161], off
	global_load_dwordx4 v[120:123], v[160:161], off offset:32
	global_load_dwordx4 v[116:119], v[160:161], off offset:64
	global_load_dwordx4 v[112:115], v[160:161], off offset:96
	global_load_dword v239, v[160:161], off offset:256
	s_waitcnt vmcnt(0)
	v_mov_b32_e32 v155, v149
	v_lshl_add_u64 v[66:67], s[82:83], 0, v[154:155]
	s_mov_b32 s70, 0x20000
	v_lshl_add_u64 v[64:65], s[92:93], 0, v[154:155]
	v_readfirstlane_b32 s77, v175
	s_cmp_lt_i32 s91, -3
	s_waitcnt vmcnt(5)
	ds_write_b128 v189, v[132:135]
	s_waitcnt vmcnt(4)
	ds_write_b128 v190, v[128:131] offset:16384
	s_waitcnt lgkmcnt(0)
	s_barrier
	ds_read_b128 v[0:3], v191 offset:16384
	ds_read_b128 v[4:7], v191 offset:20480
	s_waitcnt vmcnt(3) lgkmcnt(1)
	v_mfma_f32_32x32x16_bf16 v[16:31], v[0:3], v[124:127], 0
	ds_read_b128 v[0:3], v193 offset:16384
	ds_read_b128 v[32:35], v193 offset:20480
	s_waitcnt vmcnt(2) lgkmcnt(1)
	v_mfma_f32_32x32x16_bf16 v[16:31], v[0:3], v[120:123], v[16:31]
	v_mfma_f32_32x32x16_bf16 v[0:15], v[4:7], v[124:127], 0
	s_waitcnt lgkmcnt(0)
	v_mfma_f32_32x32x16_bf16 v[0:15], v[32:35], v[120:123], v[0:15]
	ds_read_b128 v[32:35], v194 offset:16384
	ds_read_b128 v[36:39], v194 offset:20480
	s_waitcnt vmcnt(1) lgkmcnt(1)
	v_mfma_f32_32x32x16_bf16 v[16:31], v[32:35], v[116:119], v[16:31]
	s_waitcnt lgkmcnt(0)
	v_mfma_f32_32x32x16_bf16 v[0:15], v[36:39], v[116:119], v[0:15]
	ds_read_b128 v[32:35], v195 offset:16384
	ds_read_b128 v[36:39], v195 offset:20480
	s_waitcnt vmcnt(0) lgkmcnt(1)
	v_mfma_f32_32x32x16_bf16 v[16:31], v[32:35], v[112:115], v[16:31]
	v_lshl_add_u64 v[32:33], v[66:67], 0, v[148:149]
	v_add_co_u32_e32 v32, vcc, s70, v32
	v_lshl_add_u64 v[34:35], v[64:65], 0, v[148:149]
	s_nop 0
	v_addc_co_u32_e32 v33, vcc, 0, v33, vcc
	s_waitcnt lgkmcnt(0)
	v_mfma_f32_32x32x16_bf16 v[0:15], v[36:39], v[112:115], v[0:15]
	v_add_co_u32_e32 v36, vcc, 0x20000, v34
	s_nop 3
	v_max_f32_e32 v34, v17, v17
	v_addc_co_u32_e32 v37, vcc, 0, v35, vcc
	v_max_f32_e32 v35, v16, v16
	v_max_f32_e32 v34, v35, v34
	v_max3_f32 v34, v34, v18, v19
	v_max3_f32 v34, v34, v20, v21
	v_max3_f32 v34, v34, v22, v23
	v_max3_f32 v34, v34, v24, v25
	v_max3_f32 v34, v34, v26, v27
	v_max3_f32 v34, v34, v28, v29
	v_max3_f32 v34, v34, v30, v31
	v_max3_f32 v34, v34, v0, v1
	v_max3_f32 v34, v34, v2, v3
	v_max3_f32 v34, v34, v4, v5
	v_max3_f32 v34, v34, v6, v7
	v_max3_f32 v34, v34, v8, v9
	v_max3_f32 v34, v34, v10, v11
	v_max3_f32 v34, v34, v12, v13
	v_max3_f32 v34, v34, v14, v15
	v_mov_b32_e32 v35, v34
	s_nop 1
	v_permlane32_swap_b32_e32 v34, v35
	v_max_f32_e32 v35, v35, v35
	v_max_f32_e32 v34, v34, v34
	v_max_f32_e32 v40, v34, v35
	v_add_f32_e32 v34, 0x7149f2ca, v40
	v_cmp_ge_f32_e64 s[70:71], s2, v34
	global_load_dwordx4 v[32:35], v[32:33], off
	s_nop 0
	global_load_dwordx4 v[36:39], v[36:37], off
	s_cbranch_scc1 .LBB0_1096
	v_lshl_add_u64 v[44:45], v[66:67], 0, v[148:149]
	v_add_co_u32_e32 v44, vcc, 0x40000, v44
	v_lshl_add_u64 v[42:43], v[64:65], 0, v[148:149]
	s_nop 0
	v_addc_co_u32_e32 v45, vcc, 0, v45, vcc
	v_add_co_u32_e32 v42, vcc, 0x40000, v42
	s_nop 1
	v_addc_co_u32_e32 v43, vcc, 0, v43, vcc
	global_load_dwordx4 v[128:131], v[44:45], off
	global_load_dwordx4 v[132:135], v[42:43], off
